# GDN scan: next-chunk LDS staging writes of steps 1 and 2 spread under the o-tile / state MFMAs instead of bursting before the step barrier
# speedup vs baseline: 1.0070x; 1.0070x over previous
; DI float lo16(unsigned u) { return __uint_as_float(u << 16); }
; DI float hi16(unsigned u) { return __uint_as_float(u & 0xFFFF0000u); }
; DI bf16x8 tr2(const bf16_t* p0, const bf16_t* p1) { s16x4 a = trread(p0), b = trread(p1); return __builtin_shufflevector(a, b, 0, 1, 2, 3, 4, 5, 6, 7); }
; DI f32x4 mfma16(bf16x8 a, bf16x8 b, f32x4 c) { return __builtin_amdgcn_mfma_f32_16x16x32_bf16(a, b, c, 0, 0, 0); }
; DI void gdn_scan_item(const P& p, int item, unsigned char* smem) {
;     ...
;     auto step = [&](GdnRegs& R, int c) {
;         storel(R, c & 1);
;         __syncthreads();
;         loadr(R, c + 3);
;         const bf16_t* sW = (const bf16_t*)(smem + (c & 1) * BUFB); const bf16_t* sQI = sW + 64 * 136; const bf16_t* sKO = sQI + 64 * 136; const bf16_t* sAT = sKO + 64 * 136; const bf16_t* sU = sAT + 64 * 72;
;         const float dec = sdec[c];
;         bf16x8 Bs[4];
; #pragma unroll
;         for (int ks = 0; ks < 4; ++ks) Bs[ks] = __builtin_bit_cast(bf16x8, sBS[(nt * 4 + ks) * 64 + lane]);
;         {
;             f32x4 acc = (f32x4){0.f, 0.f, 0.f, 0.f};
; #pragma unroll
;             for (int ks = 0; ks < 4; ++ks) { const bf16_t* r0 = sW + (16 * mt + l15) * 136 + 32 * ks + 4 * g; acc = mfma16(Bs[ks], ld4x2(r0, r0 + 16), acc); }
;             {
;                 const u32x2 uu = *(const u32x2*)(sU + (16 * mt + l15) * 40 + 16 * nt + 4 * g);
;                 u32x2 vv; vv.x = pk2(lo16(uu.x) - acc[0], hi16(uu.x) - acc[1]); vv.y = pk2(lo16(uu.y) - acc[2], hi16(uu.y) - acc[3]);
;                 *(u32x2*)(sVN + (16 * mt + l15) * 40 + 16 * nt + 4 * g) = vv;
;             }
;         }
;         __syncthreads();
;         bf16x8 Bv[2];
; #pragma unroll
;         for (int k2 = 0; k2 < 2; ++k2) Bv[k2] = tr2(sVN + (32 * k2 + 8 * g + q4) * 40 + 16 * nt + 4 * p4, sVN + (32 * k2 + 8 * g + 4 + q4) * 40 + 16 * nt + 4 * p4);
;         {
;             f32x4 acc = (f32x4){0.f, 0.f, 0.f, 0.f};
; #pragma unroll
;             for (int ks = 0; ks < 4; ++ks) { const bf16_t* r0 = sQI + (16 * mt + l15) * 136 + 32 * ks + 4 * g; acc = mfma16(Bs[ks], ld4x2(r0, r0 + 16), acc); }
.LBB0_507:
	s_waitcnt lgkmcnt(3)
	v_mfma_f32_16x16x32_bf16 v[104:107], v[112:115], v[224:227], 0
	v_add3_u32 v195, v134, v163, v162
	ds_read_b64 v[240:241], v195 offset:61440
	v_add_u32_e32 v189, 0x4000, v188
	v_add_u32_e32 v134, v134, v159
	s_waitcnt lgkmcnt(3)
	v_mfma_f32_16x16x32_bf16 v[104:107], v[200:203], v[228:231], v[104:107]
	v_lshlrev_b32_e32 v199, 1, v124
	v_add3_u32 v196, v134, v160, v199
	s_waitcnt lgkmcnt(2)
	v_mfma_f32_16x16x32_bf16 v[104:107], v[204:207], v[232:235], v[104:107]
	s_mov_b64 s[42:43], -1
	s_cmp_gt_u32 s26, 3
	s_waitcnt lgkmcnt(1)
	v_mfma_f32_16x16x32_bf16 v[104:107], v[208:211], v[236:239], v[104:107]
	s_waitcnt lgkmcnt(0)
	v_lshlrev_b32_e32 v110, 16, v240
	v_and_b32_e32 v108, 0xffff0000, v240
	s_nop 3
	s_nop 0
	v_sub_f32_e32 v104, v110, v104
	v_sub_f32_e32 v105, v108, v105
	v_cvt_pk_bf16_f32 v104, v104, v105
	v_lshlrev_b32_e32 v105, 16, v241
	v_sub_f32_e32 v105, v105, v106
	v_and_b32_e32 v106, 0xffff0000, v241
	v_sub_f32_e32 v106, v106, v107
	v_cvt_pk_bf16_f32 v105, v105, v106
	ds_write_b64 v123, v[104:105]
	s_waitcnt lgkmcnt(0)
	s_barrier
	v_mov_b32_e32 v212, s27
	v_and_b32_e32 v212, 1, v212
	v_mul_u32_u24_e32 v212, 0x10400, v212
	v_add_u32_e32 v212, s57, v212
	v_lshl_add_u32 v213, v120, 1, v212
	v_lshl_add_u32 v214, v122, 1, v212
	v_add3_u32 v215, v212, v119, v116
	ds_read_b64_tr_b16 v[108:109], v164
	ds_read_b64_tr_b16 v[110:111], v165
	ds_read_b64_tr_b16 v[104:105], v183
	ds_read_b64_tr_b16 v[106:107], v184
	ds_read2_b64 v[224:227], v189 offset0:128 offset1:132
	ds_read2_b64 v[228:231], v189 offset0:136 offset1:140
	ds_read2_b64 v[232:235], v189 offset0:144 offset1:148
	ds_read2_b64 v[236:239], v189 offset0:152 offset1:156
	ds_read_b128 v[240:243], v196 offset:52224
	ds_read_b128 v[244:247], v196 offset:52288
	s_waitcnt lgkmcnt(5)
	v_mfma_f32_16x16x32_bf16 v[112:115], v[112:115], v[224:227], 0
	s_waitcnt vmcnt(14)
	ds_write_b128 v213, v[28:31]
	s_waitcnt lgkmcnt(5)
	v_mfma_f32_16x16x32_bf16 v[112:115], v[200:203], v[228:231], v[112:115]
	s_waitcnt vmcnt(13)
	ds_write_b128 v213, v[32:35] offset:17408
	s_waitcnt lgkmcnt(5)
	v_mfma_f32_16x16x32_bf16 v[112:115], v[204:207], v[232:235], v[112:115]
	s_waitcnt vmcnt(12)
	ds_write_b128 v213, v[40:43] offset:34816
	s_waitcnt lgkmcnt(5)
	v_mfma_f32_16x16x32_bf16 v[112:115], v[208:211], v[236:239], v[112:115]
	s_waitcnt vmcnt(11)
	ds_write_b128 v214, v[48:51]
	s_waitcnt lgkmcnt(5)
	v_mfma_f32_16x16x32_bf16 v[112:115], v[108:111], v[240:243], v[112:115]
	s_waitcnt vmcnt(10)
	ds_write_b128 v214, v[52:55] offset:17408
	s_waitcnt lgkmcnt(5)
	v_mfma_f32_16x16x32_bf16 v[112:115], v[104:107], v[244:247], v[112:115]
	s_cbranch_scc0 .LBB0_509
	s_add_i32 s6, s22, 0xfffffe80
	s_add_i32 s7, s24, 0x80
	s_and_b64 s[4:5], s[38:39], exec
	s_cselect_b32 s4, s6, s7
	s_add_i32 s40, s4, s2
	s_mov_b64 s[42:43], 0

; DI void gdn_scan_item(const P& p, int item, unsigned char* smem) {
;     ...
;             *(u32x4*)(sW + off) = rr[k]; *(u32x4*)(sQI + off) = rr[2 + k]; *(u32x4*)(sKO + off) = rr[4 + k];
;         }
;         { const int r = tid >> 3, ch = tid & 7; *(u32x4*)(sAT + r * 72 + 8 * ch) = rr[6]; }
;         if (tid < 256) { const int r = tid >> 2, ch = tid & 3; *(u32x4*)(sU + r * 40 + 8 * ch) = rr[7]; }
;     };
;     u32x4* sBS = (u32x4*)(smem + 2 * BUFB + 5120 + 256);
;     f32x4 st[2];
;     st[0] = (f32x4){0.f, 0.f, 0.f, 0.f}; st[1] = (f32x4){0.f, 0.f, 0.f, 0.f};
;     sBS[(nt * 4 + mt) * 64 + lane] = (u32x4){0u, 0u, 0u, 0u};
;     if (tid < 36) sdec[tid] = DC[seq * 36 + tid];
;     const int sgn = dir ? -1 : 1;
;     auto step = [&](GdnRegs& R, int c) {
;         storel(R, c & 1);
;         __syncthreads();
;         loadr(R, c + 3);
;         const bf16_t* sW = (const bf16_t*)(smem + (c & 1) * BUFB); const bf16_t* sQI = sW + 64 * 136; const bf16_t* sKO = sQI + 64 * 136; const bf16_t* sAT = sKO + 64 * 136; const bf16_t* sU = sAT + 64 * 72;
;         const float dec = sdec[c];
;         bf16x8 Bs[4];
; #pragma unroll
;         for (int ks = 0; ks < 4; ++ks) Bs[ks] = __builtin_bit_cast(bf16x8, sBS[(nt * 4 + ks) * 64 + lane]);
;         {
;             f32x4 acc = (f32x4){0.f, 0.f, 0.f, 0.f};
; #pragma unroll
;             for (int ks = 0; ks < 4; ++ks) { const bf16_t* r0 = sW + (16 * mt + l15) * 136 + 32 * ks + 4 * g; acc = mfma16(Bs[ks], ld4x2(r0, r0 + 16), acc); }
;             {
;                 const u32x2 uu = *(const u32x2*)(sU + (16 * mt + l15) * 40 + 16 * nt + 4 * g);
;                 u32x2 vv; vv.x = pk2(lo16(uu.x) - acc[0], hi16(uu.x) - acc[1]); vv.y = pk2(lo16(uu.y) - acc[2], hi16(uu.y) - acc[3]);
;                 *(u32x2*)(sVN + (16 * mt + l15) * 40 + 16 * nt + 4 * g) = vv;
;             }
;         }
;         __syncthreads();
;         bf16x8 Bv[2];
; #pragma unroll
;         for (int k2 = 0; k2 < 2; ++k2) Bv[k2] = tr2(sVN + (32 * k2 + 8 * g + q4) * 40 + 16 * nt + 4 * p4, sVN + (32 * k2 + 8 * g + 4 + q4) * 40 + 16 * nt + 4 * p4);
;         {
;             f32x4 acc = (f32x4){0.f, 0.f, 0.f, 0.f};
; #pragma unroll
;             for (int ks = 0; ks < 4; ++ks) { const bf16_t* r0 = sQI + (16 * mt + l15) * 136 + 32 * ks + 4 * g; acc = mfma16(Bs[ks], ld4x2(r0, r0 + 16), acc); }
; #pragma unroll
.LBB0_511:
	v_lshl_add_u32 v134, v125, 1, s28
	v_lshlrev_b32_e32 v197, 1, v157
	v_add3_u32 v187, v134, v185, v197
	ds_read_b64_tr_b16 v[226:227], v187 offset:35904
	ds_read_b64_tr_b16 v[224:225], v187 offset:34816
	ds_read_b64_tr_b16 v[230:231], v187 offset:44608
	ds_read_b64_tr_b16 v[234:235], v187 offset:35936
	ds_read_b64_tr_b16 v[232:233], v187 offset:34848
	ds_read_b64_tr_b16 v[238:239], v187 offset:44640
	v_add3_u32 v193, v134, v186, v197
	ds_read_b64_tr_b16 v[228:229], v193 offset:34816
	ds_read_b64_tr_b16 v[236:237], v193 offset:34848
	v_pk_mul_f32 v[98:99], v[98:99], v[132:133] op_sel_hi:[1,0]
	v_pk_mul_f32 v[96:97], v[96:97], v[132:133] op_sel_hi:[1,0]
	v_pk_mul_f32 v[102:103], v[102:103], v[132:133] op_sel_hi:[1,0]
	v_pk_mul_f32 v[100:101], v[100:101], v[132:133] op_sel_hi:[1,0]
	s_waitcnt lgkmcnt(6)
	v_mfma_f32_16x16x32_bf16 v[96:99], v[224:227], v[108:111], v[96:99]
	s_waitcnt vmcnt(9)
	ds_write_b128 v214, v[64:67] offset:34816
	s_ashr_i32 s41, s40, 31
	s_lshl_b64 s[4:5], s[40:41], 10
	s_waitcnt lgkmcnt(4)
	v_mfma_f32_16x16x32_bf16 v[100:103], v[232:235], v[108:111], v[100:103]
	s_waitcnt vmcnt(3)
	ds_write_b128 v215, v[72:75] offset:52224
	s_bitcmp1_b32 s27, 0
	v_lshl_add_u64 v[108:109], v[126:127], 0, s[4:5]
	s_cselect_b32 s4, 0x10400, 0
	s_waitcnt lgkmcnt(3)
	v_mfma_f32_16x16x32_bf16 v[96:99], v[228:231], v[104:107], v[96:99]
	s_add_i32 s27, s57, s4
	v_cvt_pk_bf16_f32 v112, v112, v113
	v_cvt_pk_bf16_f32 v113, v114, v115
	s_waitcnt lgkmcnt(2)
	v_mfma_f32_16x16x32_bf16 v[100:103], v[236:239], v[104:107], v[100:103]
	global_store_dwordx2 v[108:109], v[112:113], off
	s_nop 1
	v_cvt_pk_bf16_f32 v104, v96, v97
	v_cvt_pk_bf16_f32 v105, v98, v99
	s_nop 2
	v_cvt_pk_bf16_f32 v106, v100, v101
	v_cvt_pk_bf16_f32 v107, v102, v103
	ds_write_b128 v156, v[104:107]
	s_waitcnt lgkmcnt(0)
	s_and_saveexec_b64 s[40:41], s[0:1]
	v_add3_u32 v104, s27, v161, v198
	ds_write_b128 v104, v[44:47] offset:61440
	s_or_b64 exec, exec, s[40:41]
	s_cmp_gt_u32 s26, 31
	v_readlane_b32 s12, v254, 56
	s_waitcnt lgkmcnt(0)
	s_barrier
	ds_read_b128 v[110:113], v117
	ds_read_b128 v[200:203], v117 offset:1024
	ds_read_b128 v[204:207], v117 offset:2048
	ds_read_b128 v[208:211], v117 offset:3072
	v_lshl_add_u32 v109, v121, 1, s27
	v_mov_b32_e32 v104, s21
	ds_read_b32 v108, v104 offset:4
	v_add_u32_e32 v132, v109, v162
	ds_read2_b64 v[224:227], v132 offset1:4
	ds_read2_b64 v[228:231], v132 offset0:8 offset1:12
	ds_read2_b64 v[236:239], v132 offset0:16 offset1:20
	ds_read2_b64 v[240:243], v132 offset0:24 offset1:28
	v_add_u32_e32 v109, v109, v158
	v_readlane_b32 s13, v254, 57
	s_cbranch_scc1 .LBB0_517
	v_add_co_u32_e32 v28, vcc, 0x13f5c000, v154
	s_nop 1
	v_addc_co_u32_e32 v29, vcc, 0, v155, vcc
	v_add_co_u32_e32 v32, vcc, 0x1515c000, v154
	s_nop 1
	v_addc_co_u32_e32 v33, vcc, 0, v155, vcc
	v_add_co_u32_e32 v40, vcc, 0x1635c000, v154
	global_load_dwordx4 v[28:31], v[28:29], off
	s_nop 0
	global_load_dwordx4 v[32:35], v[32:33], off
	v_addc_co_u32_e32 v41, vcc, 0, v155, vcc
	v_add_co_u32_e32 v48, vcc, 0x13f5c000, v152
	global_load_dwordx4 v[40:43], v[40:41], off
	s_nop 0
	v_addc_co_u32_e32 v49, vcc, 0, v153, vcc
	v_add_co_u32_e32 v52, vcc, 0x1515c000, v152
	s_nop 1
	v_addc_co_u32_e32 v53, vcc, 0, v153, vcc
	v_add_co_u32_e32 v64, vcc, 0x1635c000, v152
	global_load_dwordx4 v[48:51], v[48:49], off
	s_nop 0
	global_load_dwordx4 v[52:55], v[52:53], off
	v_addc_co_u32_e32 v65, vcc, 0, v153, vcc
	v_add_co_u32_e32 v72, vcc, 0x17554000, v150
	global_load_dwordx4 v[64:67], v[64:65], off
	s_nop 0
	v_addc_co_u32_e32 v73, vcc, 0, v151, vcc
	global_load_dwordx4 v[72:75], v[72:73], off
	s_and_saveexec_b64 s[40:41], s[0:1]
	s_cbranch_execz .LBB0_516
	v_lshl_add_u64 v[44:45], v[144:145], 0, s[44:45]
	v_add_co_u32_e32 v44, vcc, 0x12d5c000, v44
	s_nop 1
	v_addc_co_u32_e32 v45, vcc, 0, v45, vcc
	global_load_dwordx4 v[44:47], v[44:45], off nt

; DI float lo16(unsigned u) { return __uint_as_float(u << 16); }
; DI void gdn_scan_item(const P& p, int item, unsigned char* smem) {
;     ...
;     auto step = [&](GdnRegs& R, int c) {
;         storel(R, c & 1);
;         __syncthreads();
;         loadr(R, c + 3);
;         const bf16_t* sW = (const bf16_t*)(smem + (c & 1) * BUFB); const bf16_t* sQI = sW + 64 * 136; const bf16_t* sKO = sQI + 64 * 136; const bf16_t* sAT = sKO + 64 * 136; const bf16_t* sU = sAT + 64 * 72;
;         const float dec = sdec[c];
;         bf16x8 Bs[4];
; #pragma unroll
;         for (int ks = 0; ks < 4; ++ks) Bs[ks] = __builtin_bit_cast(bf16x8, sBS[(nt * 4 + ks) * 64 + lane]);
;         {
;             f32x4 acc = (f32x4){0.f, 0.f, 0.f, 0.f};
; #pragma unroll
;             for (int ks = 0; ks < 4; ++ks) { const bf16_t* r0 = sW + (16 * mt + l15) * 136 + 32 * ks + 4 * g; acc = mfma16(Bs[ks], ld4x2(r0, r0 + 16), acc); }
;             {
;                 const u32x2 uu = *(const u32x2*)(sU + (16 * mt + l15) * 40 + 16 * nt + 4 * g);
;                 u32x2 vv; vv.x = pk2(lo16(uu.x) - acc[0], hi16(uu.x) - acc[1]); vv.y = pk2(lo16(uu.y) - acc[2], hi16(uu.y) - acc[3]);
;                 *(u32x2*)(sVN + (16 * mt + l15) * 40 + 16 * nt + 4 * g) = vv;
;             }
;         }
;         __syncthreads();
;         bf16x8 Bv[2];
; #pragma unroll
;         for (int k2 = 0; k2 < 2; ++k2) Bv[k2] = tr2(sVN + (32 * k2 + 8 * g + q4) * 40 + 16 * nt + 4 * p4, sVN + (32 * k2 + 8 * g + 4 + q4) * 40 + 16 * nt + 4 * p4);
;         {
;             f32x4 acc = (f32x4){0.f, 0.f, 0.f, 0.f};
; #pragma unroll
;             for (int ks = 0; ks < 4; ++ks) { const bf16_t* r0 = sQI + (16 * mt + l15) * 136 + 32 * ks + 4 * g; acc = mfma16(Bs[ks], ld4x2(r0, r0 + 16), acc); }
; #pragma unroll
;             for (int k2 = 0; k2 < 2; ++k2) acc = mfma16(Bv[k2], ld8(sAT + (16 * mt + l15) * 72 + 32 * k2 + 8 * g), acc);
;             bf16_t* ob = OG + (size_t)prow(b, dir, 64 * c) * 512 + 128 * h + 32 * cq;
;             u32x2 ov; ov.x = pk2(acc[0], acc[1]); ov.y = pk2(acc[2], acc[3]);
;             *(u32x2*)(ob + sgn * ((16 * mt + l15) * 512) + 16 * nt + 4 * g) = ov;
;         }
; #pragma unroll
;         for (int j = 0; j < 2; ++j) {
;             const int dt = 2 * mt + j;
;             st[j] *= dec;
; #pragma unroll
;             for (int k2 = 0; k2 < 2; ++k2) {
.LBB0_517:
	s_waitcnt lgkmcnt(3)
	v_mfma_f32_16x16x32_bf16 v[104:107], v[110:113], v[224:227], 0
	v_add3_u32 v114, v109, v163, v162
	ds_read_b64 v[232:233], v114 offset:61440
	v_add_u32_e32 v109, v109, v159
	s_waitcnt lgkmcnt(3)
	v_mfma_f32_16x16x32_bf16 v[104:107], v[200:203], v[228:231], v[104:107]
	v_add3_u32 v109, v109, v160, v199
	s_waitcnt lgkmcnt(0)
	v_lshlrev_b32_e32 v134, 16, v232
	v_mfma_f32_16x16x32_bf16 v[104:107], v[204:207], v[236:239], v[104:107]
	v_and_b32_e32 v114, 0xffff0000, v232
	s_sub_i32 s4, s22, 64
	v_mfma_f32_16x16x32_bf16 v[104:107], v[208:211], v[240:243], v[104:107]
	s_add_i32 s5, s22, 0xfffffec0
	s_cmp_lt_u32 s26, 3
	s_movk_i32 s6, 0x8ff
	s_nop 4
	v_sub_f32_e32 v104, v134, v104
	v_sub_f32_e32 v105, v114, v105
	v_cvt_pk_bf16_f32 v104, v104, v105
	v_lshlrev_b32_e32 v105, 16, v233
	v_sub_f32_e32 v105, v105, v106
	v_and_b32_e32 v106, 0xffff0000, v233
	v_sub_f32_e32 v106, v106, v107
	v_cvt_pk_bf16_f32 v105, v105, v106
	v_add_u32_e32 v114, 0x4000, v132
	ds_write_b64 v123, v[104:105]
	s_waitcnt lgkmcnt(0)
	s_barrier
	ds_read_b64_tr_b16 v[224:225], v164
	ds_read_b64_tr_b16 v[226:227], v165
	ds_read_b64_tr_b16 v[228:229], v183
	ds_read_b64_tr_b16 v[230:231], v184
	ds_read2_b64 v[232:235], v114 offset0:128 offset1:132
	ds_read2_b64 v[236:239], v114 offset0:136 offset1:140
	ds_read2_b64 v[240:243], v114 offset0:144 offset1:148
	ds_read2_b64 v[244:247], v114 offset0:152 offset1:156
	ds_read_b128 v[248:251], v109 offset:52224
	s_waitcnt lgkmcnt(4)
	v_mfma_f32_16x16x32_bf16 v[110:113], v[110:113], v[232:235], 0
	ds_read_b128 v[232:235], v109 offset:52288
	s_waitcnt vmcnt(8)
	ds_write_b128 v190, v[56:59]
	s_cselect_b32 s6, 0xff, s6
	s_cselect_b32 s7, s4, s5
	s_waitcnt lgkmcnt(5)
	v_mfma_f32_16x16x32_bf16 v[110:113], v[200:203], v[236:239], v[110:113]
	s_waitcnt vmcnt(7)
	ds_write_b128 v190, v[60:63] offset:17408
	s_cselect_b32 s8, s3, s2
	s_add_i32 s4, s6, s24
	s_waitcnt lgkmcnt(5)
	v_mfma_f32_16x16x32_bf16 v[110:113], v[204:207], v[240:243], v[110:113]
	s_waitcnt vmcnt(6)
	ds_write_b128 v190, v[68:71] offset:34816
	s_add_i32 s6, s4, 0xfffff741
	s_and_b64 s[4:5], s[38:39], exec
	s_waitcnt lgkmcnt(5)
	v_mfma_f32_16x16x32_bf16 v[110:113], v[208:211], v[244:247], v[110:113]
	s_waitcnt vmcnt(5)
	ds_write_b128 v192, v[76:79]
	s_cselect_b32 s4, s7, s6
	s_add_i32 s4, s4, s8
	s_waitcnt lgkmcnt(5)
	v_mfma_f32_16x16x32_bf16 v[110:113], v[224:227], v[248:251], v[110:113]
	s_waitcnt vmcnt(4)
	ds_write_b128 v192, v[80:83] offset:17408
	s_ashr_i32 s5, s4, 31
	s_lshl_b64 s[4:5], s[4:5], 10
	s_waitcnt lgkmcnt(5)
	v_mfma_f32_16x16x32_bf16 v[110:113], v[228:231], v[232:235], v[110:113]
	v_mul_f32_e64 v98, v98, v108
	v_mul_f32_e64 v99, v99, v108
	v_pk_mul_f32 v[96:97], v[96:97], v[108:109] op_sel_hi:[1,0]
	v_lshl_add_u32 v109, v125, 1, s27
	s_nop 3
	v_cvt_pk_bf16_f32 v110, v110, v111
	v_cvt_pk_bf16_f32 v111, v112, v113
	v_lshl_add_u64 v[112:113], v[126:127], 0, s[4:5]
	global_store_dwordx2 v[112:113], v[110:111], off
	v_add3_u32 v114, v109, v185, v197
	ds_read_b64_tr_b16 v[238:239], v114 offset:35904
	ds_read_b64_tr_b16 v[236:237], v114 offset:34816
	ds_read_b64_tr_b16 v[240:241], v114 offset:34848
	ds_read_b64_tr_b16 v[246:247], v114 offset:44608
	ds_read_b64_tr_b16 v[242:243], v114 offset:35936
	ds_read_b64_tr_b16 v[250:251], v114 offset:44640
	s_waitcnt lgkmcnt(4)
	v_mfma_f32_16x16x32_bf16 v[96:99], v[236:239], v[224:227], v[96:99]
	s_waitcnt vmcnt(3)
	ds_write_b128 v192, v[84:87] offset:34816
	v_add3_u32 v109, v109, v186, v197
	ds_read_b64_tr_b16 v[244:245], v109 offset:34816
	ds_read_b64_tr_b16 v[248:249], v109 offset:34848
	v_pk_mul_f32 v[102:103], v[102:103], v[108:109] op_sel_hi:[1,0]
	v_pk_mul_f32 v[100:101], v[100:101], v[108:109] op_sel_hi:[1,0]
	s_waitcnt lgkmcnt(1)
	v_mfma_f32_16x16x32_bf16 v[96:99], v[244:247], v[228:231], v[96:99]
	s_waitcnt vmcnt(2)
	ds_write_b128 v194, v[92:95] offset:52224
	v_mfma_f32_16x16x32_bf16 v[100:103], v[240:243], v[224:227], v[100:103]
	s_waitcnt lgkmcnt(1)
	v_mfma_f32_16x16x32_bf16 v[100:103], v[248:251], v[228:231], v[100:103]
	s_nop 3
	s_nop 0
	v_cvt_pk_bf16_f32 v104, v96, v97
	v_cvt_pk_bf16_f32 v105, v98, v99
	s_nop 1
	v_cvt_pk_bf16_f32 v106, v100, v101
	v_cvt_pk_bf16_f32 v107, v102, v103
	ds_write_b128 v156, v[104:107]
	s_waitcnt lgkmcnt(0)
	s_and_saveexec_b64 s[40:41], s[0:1]
	ds_write_b128 v191, v[88:91] offset:61440
	s_or_b64 exec, exec, s[40:41]
	s_cmp_gt_u32 s26, 30
	s_waitcnt lgkmcnt(0)
	s_barrier
	ds_read_b128 v[112:115], v117
	ds_read_b128 v[248:251], v117 offset:1024
	ds_read_b128 v[198:201], v117 offset:2048
	ds_read_b128 v[202:205], v117 offset:3072
	ds_read2_b64 v[224:227], v188 offset1:4
	ds_read2_b64 v[228:231], v188 offset0:8 offset1:12
	ds_read2_b64 v[232:235], v188 offset0:16 offset1:20
	ds_read2_b64 v[236:239], v188 offset0:24 offset1:28
	ds_read_b64 v[240:241], v195 offset:61440
	v_mov_b32_e32 v104, s21
	ds_read_b32 v132, v104 offset:8
	s_cbranch_scc1 .LBB0_523
	v_add_co_u32_e32 v56, vcc, 0x13f60000, v154
	s_nop 1
	v_addc_co_u32_e32 v57, vcc, 0, v155, vcc
	v_add_co_u32_e32 v60, vcc, 0x15160000, v154
	s_nop 1
	v_addc_co_u32_e32 v61, vcc, 0, v155, vcc
	v_add_co_u32_e32 v68, vcc, 0x16360000, v154
	global_load_dwordx4 v[56:59], v[56:57], off
	s_nop 0
	global_load_dwordx4 v[60:63], v[60:61], off
	v_addc_co_u32_e32 v69, vcc, 0, v155, vcc
	v_add_co_u32_e32 v76, vcc, 0x13f60000, v152
	global_load_dwordx4 v[68:71], v[68:69], off
	s_nop 0
	v_addc_co_u32_e32 v77, vcc, 0, v153, vcc
	v_add_co_u32_e32 v80, vcc, 0x15160000, v152
	s_nop 1
	v_addc_co_u32_e32 v81, vcc, 0, v153, vcc
	v_add_co_u32_e32 v84, vcc, 0x16360000, v152
	global_load_dwordx4 v[76:79], v[76:77], off
	s_nop 0
	global_load_dwordx4 v[80:83], v[80:81], off
	v_addc_co_u32_e32 v85, vcc, 0, v153, vcc
	v_add_co_u32_e32 v92, vcc, 0x17556000, v150
	global_load_dwordx4 v[84:87], v[84:85], off
	s_nop 0
	v_addc_co_u32_e32 v93, vcc, 0, v151, vcc
	global_load_dwordx4 v[92:95], v[92:93], off
	s_and_saveexec_b64 s[40:41], s[0:1]
	s_cbranch_execz .LBB0_522
	v_lshl_add_u64 v[88:89], v[144:145], 0, s[44:45]
	v_add_co_u32_e32 v88, vcc, 0x12d60000, v88
	s_nop 1
	v_addc_co_u32_e32 v89, vcc, 0, v89, vcc
	global_load_dwordx4 v[88:91], v[88:89], off nt
